# grid seams: non-leader workgroups wait on the cross-XCD release generation directly (one hand-off hop fewer per seam); plus the early write-back by the second-to-last arriver
# speedup vs baseline: 1.0106x; 1.0106x over previous
; __device__ __forceinline__ unsigned xb_ld(unsigned* p)              { return __hip_atomic_load(p, __ATOMIC_RELAXED, __HIP_MEMORY_SCOPE_AGENT); }
; __device__ __forceinline__ unsigned xb_add(unsigned* p, unsigned v) { return __hip_atomic_fetch_add(p, v, __ATOMIC_RELAXED, __HIP_MEMORY_SCOPE_AGENT); }
; #define XB_SPIN(cond, bar) do { unsigned _sp = 0; while (cond) { __builtin_amdgcn_s_sleep(1); \
;     if ((++_sp & 255u) == 0u) { if (xb_ld(&(bar)[XB_TMO])) break; if (_sp > XB_SPIN_CAP) { atomicAdd(&(bar)[XB_TMO], 1u); break; } } } } while (0)
; __device__ __forceinline__ void xcd_barrier(const XcdBarrier& b, const int wv) {
;     ...
;             const unsigned og = xb_add(&bar[XB_TOP], 1u);
;             const unsigned tg = og / nx;
;             if (og + 1u == (tg + 1u) * nx) xb_add(&bar[XB_TOPGEN], 1u);
;             else XB_SPIN(xb_ld(&bar[XB_TOPGEN]) == tg, bar);
;     ...
;         } else {
;             XB_SPIN(xb_ld(&bar[XB_XGEN(b.x)]) == gen, bar);
;             __builtin_amdgcn_fence(__ATOMIC_ACQUIRE, "agent");
;             asm volatile("s_waitcnt vmcnt(0)" ::: "memory");
;         }
.Lpf2_0:
	s_waitcnt lgkmcnt(0)
	v_mov_b32_e32 v0, 0x7100
	global_load_dword v0, v0, s[6:7] offset:1024 sc1
	s_add_u32 s18, s6, 0x7500
	s_addc_u32 s19, s7, 0
	s_waitcnt vmcnt(0)
	v_cmp_eq_u32_e32 vcc, v0, v1
	s_and_saveexec_b64 s[14:15], vcc
	s_cbranch_execz .Lseam1_341
	s_add_u32 s16, s6, 0x4200
	s_addc_u32 s17, s7, 0
	s_mov_b32 s3, 1
	s_mov_b64 s[20:21], 0
	v_mov_b32_e32 v0, 0
	s_branch .Lseam1_332

; __device__ __forceinline__ unsigned xb_ld(unsigned* p)              { return __hip_atomic_load(p, __ATOMIC_RELAXED, __HIP_MEMORY_SCOPE_AGENT); }
; __device__ __forceinline__ unsigned xb_add(unsigned* p, unsigned v) { return __hip_atomic_fetch_add(p, v, __ATOMIC_RELAXED, __HIP_MEMORY_SCOPE_AGENT); }
; #define XB_SPIN(cond, bar) do { unsigned _sp = 0; while (cond) { __builtin_amdgcn_s_sleep(1); \
;     if ((++_sp & 255u) == 0u) { if (xb_ld(&(bar)[XB_TMO])) break; if (_sp > XB_SPIN_CAP) { atomicAdd(&(bar)[XB_TMO], 1u); break; } } } } while (0)
; __device__ __forceinline__ void xcd_barrier(const XcdBarrier& b, const int wv) {
;     ...
;             const unsigned og = xb_add(&bar[XB_TOP], 1u);
;             const unsigned tg = og / nx;
;             if (og + 1u == (tg + 1u) * nx) xb_add(&bar[XB_TOPGEN], 1u);
;             else XB_SPIN(xb_ld(&bar[XB_TOPGEN]) == tg, bar);
;     ...
;         } else {
;             XB_SPIN(xb_ld(&bar[XB_XGEN(b.x)]) == gen, bar);
;             __builtin_amdgcn_fence(__ATOMIC_ACQUIRE, "agent");
;             asm volatile("s_waitcnt vmcnt(0)" ::: "memory");
;         }
.Lpf2_4:
	s_waitcnt lgkmcnt(0)
	v_mov_b32_e32 v0, 0x7100
	global_load_dword v0, v0, s[10:11] offset:1024 sc1
	s_add_u32 s20, s10, 0x7500
	s_addc_u32 s21, s11, 0
	s_waitcnt vmcnt(0)
	v_cmp_eq_u32_e32 vcc, v0, v1
	s_and_saveexec_b64 s[16:17], vcc
	s_cbranch_execz .LBB0_740
	s_add_u32 s18, s10, 0x4200
	s_addc_u32 s19, s11, 0
	s_mov_b32 s3, 1
	s_mov_b64 s[22:23], 0
	v_mov_b32_e32 v0, 0
	s_branch .LBB0_731

; __device__ __forceinline__ unsigned xb_ld(unsigned* p)              { return __hip_atomic_load(p, __ATOMIC_RELAXED, __HIP_MEMORY_SCOPE_AGENT); }
; __device__ __forceinline__ unsigned xb_add(unsigned* p, unsigned v) { return __hip_atomic_fetch_add(p, v, __ATOMIC_RELAXED, __HIP_MEMORY_SCOPE_AGENT); }
; #define XB_SPIN(cond, bar) do { unsigned _sp = 0; while (cond) { __builtin_amdgcn_s_sleep(1); \
;     if ((++_sp & 255u) == 0u) { if (xb_ld(&(bar)[XB_TMO])) break; if (_sp > XB_SPIN_CAP) { atomicAdd(&(bar)[XB_TMO], 1u); break; } } } } while (0)
; __device__ __forceinline__ void xcd_barrier(const XcdBarrier& b, const int wv) {
;     ...
;             const unsigned og = xb_add(&bar[XB_TOP], 1u);
;             const unsigned tg = og / nx;
;             if (og + 1u == (tg + 1u) * nx) xb_add(&bar[XB_TOPGEN], 1u);
;             else XB_SPIN(xb_ld(&bar[XB_TOPGEN]) == tg, bar);
;     ...
;         } else {
;             XB_SPIN(xb_ld(&bar[XB_XGEN(b.x)]) == gen, bar);
;             __builtin_amdgcn_fence(__ATOMIC_ACQUIRE, "agent");
;             asm volatile("s_waitcnt vmcnt(0)" ::: "memory");
;         }
.Lpf2_6:
	s_waitcnt lgkmcnt(0)
	v_mov_b32_e32 v0, 0x7100
	global_load_dword v0, v0, s[12:13] offset:1024 sc1
	s_add_u32 s22, s12, 0x7500
	s_addc_u32 s23, s13, 0
	s_waitcnt vmcnt(0)
	v_cmp_eq_u32_e32 vcc, v0, v1
	s_and_saveexec_b64 s[18:19], vcc
	s_cbranch_execz .LBB0_873
	s_add_u32 s20, s12, 0x4200
	s_addc_u32 s21, s13, 0
	s_mov_b32 s3, 1
	s_mov_b64 s[24:25], 0
	v_mov_b32_e32 v0, 0
	s_branch .LBB0_864

; __device__ __forceinline__ unsigned xb_ld(unsigned* p)              { return __hip_atomic_load(p, __ATOMIC_RELAXED, __HIP_MEMORY_SCOPE_AGENT); }
; __device__ __forceinline__ unsigned xb_add(unsigned* p, unsigned v) { return __hip_atomic_fetch_add(p, v, __ATOMIC_RELAXED, __HIP_MEMORY_SCOPE_AGENT); }
; #define XB_SPIN(cond, bar) do { unsigned _sp = 0; while (cond) { __builtin_amdgcn_s_sleep(1); \
;     if ((++_sp & 255u) == 0u) { if (xb_ld(&(bar)[XB_TMO])) break; if (_sp > XB_SPIN_CAP) { atomicAdd(&(bar)[XB_TMO], 1u); break; } } } } while (0)
; __device__ __forceinline__ void xcd_barrier(const XcdBarrier& b, const int wv) {
;     ...
;             const unsigned og = xb_add(&bar[XB_TOP], 1u);
;             const unsigned tg = og / nx;
;             if (og + 1u == (tg + 1u) * nx) xb_add(&bar[XB_TOPGEN], 1u);
;             else XB_SPIN(xb_ld(&bar[XB_TOPGEN]) == tg, bar);
;     ...
;         } else {
;             XB_SPIN(xb_ld(&bar[XB_XGEN(b.x)]) == gen, bar);
;             __builtin_amdgcn_fence(__ATOMIC_ACQUIRE, "agent");
;             asm volatile("s_waitcnt vmcnt(0)" ::: "memory");
;         }
.Lpf2_16:
	s_waitcnt lgkmcnt(0)
	v_mov_b32_e32 v0, 0x7100
	global_load_dword v0, v0, s[8:9] offset:1024 sc1
	s_add_u32 s18, s8, 0x7500
	s_addc_u32 s19, s9, 0
	s_waitcnt vmcnt(0)
	v_cmp_eq_u32_e32 vcc, v0, v1
	s_and_saveexec_b64 s[14:15], vcc
	s_cbranch_execz .LBB0_2060
	s_add_u32 s16, s8, 0x4200
	s_addc_u32 s17, s9, 0
	s_mov_b32 s3, 1
	s_mov_b64 s[20:21], 0
	v_mov_b32_e32 v0, 0
	s_branch .LBB0_2050
